# W_out GEMM also walks each XCD's row tiles newest-first (on top of the down GEMM reversal)
# speedup vs baseline: 1.0072x; 1.0030x over previous
.LBB0_9:
	s_ashr_i32 s73, s2, 31
	v_writelane_b32 v253, s4, 4
	s_lshr_b32 s4, s73, 29
	s_add_i32 s4, s2, s4
	s_ashr_i32 s22, s4, 3
	s_and_b32 s4, s4, -8
	s_sub_i32 s23, s2, s4
	s_add_u32 s62, s0, 0x4200
	s_addc_u32 s63, s1, 0
	s_add_u32 s4, s0, 0x4400
	s_addc_u32 s5, s1, 0
	v_writelane_b32 v253, s4, 5
	s_load_dword s24, s[60:61], 0xd0
	v_mov_b32_e32 v189, 0
	v_writelane_b32 v253, s5, 6
	s_add_u32 s4, s0, 0x4500
	s_addc_u32 s5, s1, 0
	v_writelane_b32 v253, s4, 7
	v_mov_b32_e32 v214, 0x3c0881c4
	v_mov_b32_e32 v215, 0xbab64f3b
	v_writelane_b32 v253, s5, 8
	s_add_u32 s4, s0, 0x4600
	s_addc_u32 s5, s1, 0
	v_writelane_b32 v253, s4, 9
	v_mov_b32_e32 v191, 0x3727c5ac
	v_mov_b32_e32 v216, 0x260
	v_writelane_b32 v253, s5, 10
	s_add_u32 s4, s0, 0x4700
	s_addc_u32 s5, s1, 0
	v_writelane_b32 v253, s4, 11
	v_mov_b32_e32 v227, 1
	v_mov_b32_e32 v252, 0xc0135761
	v_writelane_b32 v253, s5, 12
	s_add_u32 s4, s0, 0x4800
	s_addc_u32 s5, s1, 0
	s_add_u32 s68, s0, 0x4900
	v_writelane_b32 v253, s4, 13
	s_addc_u32 s69, s1, 0
	v_mov_b32_e32 v190, 0x43dc0000
	v_writelane_b32 v253, s5, 14
	s_add_u32 s4, s0, 0x4a00
	s_addc_u32 s5, s1, 0
	s_add_u32 s6, s0, 0x4b00
	s_addc_u32 s7, s1, 0
	s_add_u32 s8, s0, 0x4c00
	s_addc_u32 s9, s1, 0
	s_add_u32 s10, s0, 0x4d00
	s_addc_u32 s11, s1, 0
	s_add_u32 s12, s0, 0x4e00
	s_addc_u32 s13, s1, 0
	s_add_u32 s88, s0, 0x4f00
	s_addc_u32 s89, s1, 0
	s_add_u32 s90, s0, 0x5000
	s_addc_u32 s91, s1, 0
	s_add_u32 s92, s0, 0x5100
	s_addc_u32 s93, s1, 0
	s_add_u32 s94, s0, 0x5200
	s_addc_u32 s95, s1, 0
	s_add_u32 s96, s0, 0x5300
	s_addc_u32 s97, s1, 0
	s_cmp_eq_u32 s3, 15
	s_cselect_b64 s[16:17], -1, 0
	v_writelane_b32 v253, s16, 15
	s_cmp_eq_u32 s3, 14
	v_mov_b32_e32 v217, 0x7f800000
	v_writelane_b32 v253, s17, 16
	s_cselect_b64 s[16:17], -1, 0
	v_writelane_b32 v253, s16, 17
	s_cmp_eq_u32 s3, 13
	v_mov_b32_e32 v219, 0x7fc00000
	v_writelane_b32 v253, s17, 18
	s_cselect_b64 s[16:17], -1, 0
	v_writelane_b32 v253, s16, 19
	s_cmp_eq_u32 s3, 12
	v_mov_b32_e32 v218, 0x3c800000
	v_writelane_b32 v253, s17, 20
	s_cselect_b64 s[16:17], -1, 0
	v_writelane_b32 v253, s16, 21
	s_cmp_eq_u32 s3, 11
	v_mov_b32_e32 v193, 0x10000
	v_writelane_b32 v253, s17, 22
	s_cselect_b64 s[16:17], -1, 0
	v_writelane_b32 v253, s16, 23
	s_cmp_eq_u32 s3, 10
	s_mov_b32 s87, 0x8000
	v_writelane_b32 v253, s17, 24
	s_cselect_b64 s[16:17], -1, 0
	v_writelane_b32 v253, s16, 25
	s_cmp_eq_u32 s3, 9
	s_movk_i32 s33, 0x7fff
	v_writelane_b32 v253, s17, 26
	s_cselect_b64 s[16:17], -1, 0
	v_writelane_b32 v253, s16, 27
	s_cmp_eq_u32 s3, 8
	s_movk_i32 s85, 0x3dff
	v_writelane_b32 v253, s17, 28
	s_cselect_b64 s[16:17], -1, 0
	v_writelane_b32 v253, s16, 29
	s_cmp_eq_u32 s3, 7
	s_mov_b32 s65, 0
	v_writelane_b32 v253, s17, 30
	s_cselect_b64 s[16:17], -1, 0
	v_writelane_b32 v253, s16, 31
	s_cmp_eq_u32 s3, 6
	s_mov_b64 s[28:29], 0x100000
	v_writelane_b32 v253, s17, 32
	s_cselect_b64 s[16:17], -1, 0
	v_writelane_b32 v253, s16, 33
	s_cmp_eq_u32 s3, 5
	s_mov_b64 s[30:31], 0x80
	v_writelane_b32 v253, s17, 34
	s_cselect_b64 s[16:17], -1, 0
	v_writelane_b32 v253, s16, 35
	s_cmp_eq_u32 s3, 4
	s_mov_b64 s[34:35], 0x40080
	v_writelane_b32 v253, s17, 36
	s_cselect_b64 s[16:17], -1, 0
	v_writelane_b32 v253, s16, 37
	s_cmp_eq_u32 s3, 3
	s_mov_b32 s72, 0x3c800000
	v_writelane_b32 v253, s17, 38
	s_cselect_b64 s[16:17], -1, 0
	v_writelane_b32 v253, s16, 39
	s_cmp_eq_u32 s3, 2
	s_mov_b64 s[82:83], 0x800
	v_writelane_b32 v253, s17, 40
	s_cselect_b64 s[16:17], -1, 0
	v_writelane_b32 v253, s16, 41
	s_cmp_eq_u32 s3, 1
	s_mov_b32 s70, 0xffff
	v_writelane_b32 v253, s17, 42
	s_cselect_b64 s[16:17], -1, 0
	v_writelane_b32 v253, s16, 43
	s_cmp_eq_u32 s3, 0
	s_nop 0
	v_writelane_b32 v253, s17, 44
	s_cselect_b64 s[16:17], -1, 0
	s_lshl_b32 s3, s3, 8
	s_add_u32 s3, s14, s3
	v_writelane_b32 v253, s16, 45
	s_addc_u32 s14, s15, 0
	s_nop 0
	v_writelane_b32 v253, s17, 46
	s_add_u32 s16, s3, 0x1400
	s_addc_u32 s17, s14, 0
	v_writelane_b32 v253, s16, 47
	s_nop 1
	v_writelane_b32 v253, s17, 48
	s_add_u32 s16, s3, 0x2400
	s_addc_u32 s17, s14, 0
	v_writelane_b32 v253, s16, 49
	s_add_u32 s14, s0, 0x7400
	s_addc_u32 s15, s1, 0
	v_writelane_b32 v253, s17, 50
	v_writelane_b32 v253, s14, 51
	s_add_u32 s0, s0, 0x7500
	s_addc_u32 s1, s1, 0
	v_writelane_b32 v253, s15, 52
	v_writelane_b32 v253, s0, 53
	s_cmpk_gt_i32 s2, 0x9ff
	s_movk_i32 s16, 0x501
	v_writelane_b32 v253, s1, 54
	s_cselect_b64 s[0:1], -1, 0
	v_writelane_b32 v253, s0, 55
	s_bfe_u32 s3, s2, 0x30003
	s_nop 0
	v_writelane_b32 v253, s1, 56
	s_and_b32 s1, s2, 7
	s_mul_i32 s0, s1, 40
	s_or_b32 s0, s3, s0
	v_writelane_b32 v253, s0, 57
	s_bfe_u32 s0, s2, 0x20006
	v_writelane_b32 v253, s0, 58
	s_and_b32 s0, s2, 56
	s_cmpk_lt_i32 s2, 0x500
	v_writelane_b32 v253, s0, 59
	s_cselect_b64 s[14:15], -1, 0
	v_writelane_b32 v253, s14, 60
	s_cmp_lt_u32 s2, 32
	s_mulk_i32 s1, 0x140
	v_writelane_b32 v253, s15, 61
	s_cselect_b64 s[14:15], -1, 0
	s_and_b32 s3, s2, 15
	v_writelane_b32 v253, s14, 62
	s_cmp_gt_u32 s2, 15
	s_nop 0
	v_writelane_b32 v253, s15, 63
	s_cselect_b64 s[14:15], -1, 0
	v_writelane_b32 v254, s14, 0
	s_lshl_b32 s0, s3, 13
	s_add_i32 s0, s0, 0x8000
	v_writelane_b32 v254, s15, 1
	v_writelane_b32 v254, s0, 2
	s_waitcnt lgkmcnt(0)
	s_lshl_b32 s0, s24, 3
	s_addk_i32 s0, 0xff00
	v_writelane_b32 v254, s0, 3
	s_lshl_b32 s14, s2, 11
	v_writelane_b32 v254, s14, 4
	s_lshl_b32 s14, s2, 3
	s_lshl_b32 s74, s2, 14
	s_lshl_b32 s0, s3, 16
	v_writelane_b32 v254, s14, 5
	s_addk_i32 s14, 0xff00
	s_cmpk_lt_i32 s2, 0x2800
	v_writelane_b32 v254, s14, 6
	s_cselect_b64 s[14:15], -1, 0
	v_writelane_b32 v254, s14, 7
	s_cmpk_lt_i32 s2, 0xa00
	s_nop 0
	v_writelane_b32 v254, s15, 8
	s_cselect_b64 s[14:15], -1, 0
	v_writelane_b32 v254, s14, 9
	s_cmp_lt_i32 s23, 0
	s_cselect_b32 s16, s16, 0x500
	v_writelane_b32 v254, s15, 10
	s_movk_i32 s14, 0x141
	s_cselect_b32 s14, s14, 0x140
	s_mul_i32 s14, s23, s14
	s_movk_i32 s15, 0xa1
	s_cselect_b32 s15, s15, 0xa0
	s_add_i32 s17, s14, s22
	s_ashr_i32 s18, s17, 31
	s_lshr_b32 s14, s18, 26
	s_add_i32 s14, s17, s14
	s_and_b32 s19, s14, 0xffc0
	s_sub_i32 s19, s17, s19
	s_bfe_i32 s20, s19, 0x80000
	s_bfe_u32 s20, s20, 0x3000c
	s_add_i32 s20, s19, s20
	s_and_b32 s21, s20, 0xf8
	s_sub_i32 s19, s19, s21
	s_ashr_i32 s14, s14, 6
	s_lshl_b32 s14, s14, 3
	s_sext_i32_i8 s19, s19
	s_add_i32 s14, s14, s19
	v_writelane_b32 v254, s14, 11
	s_mul_i32 s14, s23, s15
	s_add_i32 s14, s14, s22
	s_ashr_i32 s15, s14, 31
	s_lshr_b32 s15, s15, 27
	s_add_i32 s15, s14, s15
	s_and_b32 s19, s15, 0xffe0
	s_sub_i32 s14, s14, s19
	s_bfe_i32 s19, s14, 0x80000
	s_bfe_u32 s19, s19, 0x3000c
	s_add_i32 s19, s14, s19
	s_mul_i32 s16, s23, s16
	s_and_b32 s21, s19, 0xf8
	s_add_i32 s16, s16, s22
	s_sub_i32 s14, s14, s21
	s_ashr_i32 s21, s16, 31
	s_lshr_b32 s21, s21, 25
	s_bfe_i32 s20, s20, 0x80000
	v_writelane_b32 v254, s23, 12
	s_add_i32 s21, s16, s21
	s_sext_i32_i16 s20, s20
	s_ashr_i32 s15, s15, 5
	s_bfe_i32 s19, s19, 0x80000
	v_writelane_b32 v254, s22, 13
	s_and_b32 s22, s21, 0xff80
	s_ashr_i32 s20, s20, 3
	s_lshl_b32 s15, s15, 3
	s_sext_i32_i16 s19, s19
	s_sext_i32_i8 s14, s14
	s_sub_i32 s16, s16, s22
	v_writelane_b32 v254, s20, 14
	s_add_i32 s26, s15, s14
	s_mul_i32 s98, s26, 0xcccd
	s_lshr_b32 s98, s98, 21
	s_mul_i32 s98, s98, 0x50
	s_addk_i32 s98, 0x27
	s_sub_i32 s26, s98, s26
	s_ashr_i32 s14, s19, 3
	s_bfe_i32 s22, s16, 0x80000
	v_writelane_b32 v254, s14, 15
	s_lshr_b32 s14, s19, 3
	s_bfe_u32 s22, s22, 0x3000c
	s_bfe_i64 s[14:15], s[14:15], 0x100000
	s_add_i32 s22, s16, s22
	s_lshl_b64 s[14:15], s[14:15], 19
	s_and_b32 s23, s22, 0xf8
	v_writelane_b32 v254, s14, 16
	s_sub_i32 s16, s16, s23
	s_sext_i32_i8 s16, s16
	v_writelane_b32 v254, s15, 17
	s_ashr_i32 s14, s21, 7
	s_bfe_i32 s15, s22, 0x80000
	s_lshl_b32 s14, s14, 3
	s_sext_i32_i16 s15, s15
	s_add_i32 s20, s14, s16
	s_ashr_i32 s14, s15, 3
	v_writelane_b32 v254, s14, 18
	s_lshr_b32 s14, s15, 3
	s_bfe_i64 s[14:15], s[14:15], 0x100000
	s_lshl_b64 s[14:15], s[14:15], 18
	v_writelane_b32 v254, s14, 19
	s_ashr_i32 s27, s26, 31
	s_lshl_b64 s[22:23], s[26:27], 19
	v_writelane_b32 v254, s15, 20
	s_add_i32 s14, s20, 0xffffff80
	s_lshr_b32 s14, s14, 5
	s_ashr_i32 s15, s20, 3
	s_mov_b32 s16, s26
	s_cmpk_lt_i32 s20, 0x80
	v_writelane_b32 v254, s16, 21
	s_cselect_b32 s14, s15, s14
	s_lshr_b32 s15, s18, 27
	v_writelane_b32 v254, s17, 22
	s_add_i32 s16, s17, s15
	s_and_b32 s15, s16, 0xffe0
	s_sub_i32 s15, s17, s15
	s_bfe_i32 s17, s15, 0x80000
	s_bfe_u32 s17, s17, 0x3000c
	v_writelane_b32 v254, s22, 23
	s_add_i32 s17, s15, s17
	s_and_b32 s18, s17, 0xf8
	v_writelane_b32 v254, s23, 24
	s_sub_i32 s18, s15, s18
	v_writelane_b32 v254, s1, 25
	s_mul_i32 s1, s3, 0x14000
	s_ashr_i32 s15, s14, 31
	v_writelane_b32 v254, s1, 26
	s_lshl_b64 s[14:15], s[14:15], 22
	v_writelane_b32 v254, s14, 27
	s_ashr_i32 s1, s16, 5
	s_bfe_i32 s3, s17, 0x80000
	v_writelane_b32 v254, s15, 28
	s_lshl_b32 s1, s1, 3
	s_sext_i32_i16 s3, s3
	s_sext_i32_i8 s14, s18
	s_add_i32 s16, s1, s14
	s_mul_i32 s98, s16, 0xcccd
	s_lshr_b32 s98, s98, 22
	s_mul_i32 s98, s98, 0xa0
	s_addk_i32 s98, 0x4f
	s_sub_i32 s16, s98, s16
	s_lshr_b32 s14, s3, 3
	s_ashr_i32 s1, s3, 3
	s_bfe_i64 s[14:15], s[14:15], 0x100000
	v_writelane_b32 v254, s1, 29
	s_lshl_b64 s[14:15], s[14:15], 19
	v_writelane_b32 v254, s14, 30
	s_ashr_i32 s21, s20, 31
	s_ashr_i32 s17, s16, 31
	v_writelane_b32 v254, s15, 31
	s_mov_b32 s14, s20
	v_writelane_b32 v254, s14, 32
	s_add_i32 s1, s16, 0xffffff80
	s_lshr_b32 s1, s1, 5
	v_writelane_b32 v254, s15, 33
	s_lshl_b64 s[14:15], s[20:21], 10
	v_writelane_b32 v254, s14, 34
	s_ashr_i32 s3, s16, 3
	s_mov_b64 s[26:27], 0x40000
	v_writelane_b32 v254, s15, 35
	s_lshl_b64 s[14:15], s[16:17], 19
	v_writelane_b32 v254, s14, 36
	s_cmpk_lt_i32 s16, 0x80
	s_mov_b64 s[20:21], 0xc0000
	v_writelane_b32 v254, s15, 37
	s_mov_b32 s14, s16
	v_writelane_b32 v254, s14, 38
	v_cmp_eq_u32_e64 s[16:17], 0, v0
	s_mov_b64 s[22:23], 0x80000
	v_writelane_b32 v254, s15, 39
	s_cselect_b32 s14, s3, s1
	s_ashr_i32 s15, s14, 31
	s_lshl_b64 s[14:15], s[14:15], 21
	v_writelane_b32 v254, s14, 40
	s_lshl_b32 s1, s24, 8
	s_addk_i32 s1, 0xe000
	v_writelane_b32 v254, s15, 41
	v_writelane_b32 v254, s1, 42
	s_lshl_b32 s1, s24, 4
	s_addk_i32 s1, 0xfe00
	v_writelane_b32 v254, s1, 43
	s_lshl_b32 s1, s24, 10
	s_addk_i32 s1, 0x8000
	v_writelane_b32 v254, s1, 44
	s_lshl_b32 s0, s0, 2
	v_writelane_b32 v254, s0, 45
	s_add_i32 s0, 0, 0x12200
	v_writelane_b32 v254, s0, 46
	s_add_i32 s0, 0, 0x11200
	v_writelane_b32 v254, s0, 47
	s_add_i32 s0, 0, 0x10200
	v_writelane_b32 v254, s0, 48
	s_add_i32 s0, 0, 0x10004
	v_writelane_b32 v254, s0, 49
	s_add_i32 s0, 0, 0x10008
	v_writelane_b32 v254, s0, 50
	s_add_i32 s0, 0, 0x1000c
	v_writelane_b32 v254, s0, 51
	s_add_i32 s0, 0, 0x10010
	v_writelane_b32 v254, s0, 52
	s_add_i32 s0, 0, 0x10014
	v_writelane_b32 v254, s0, 53
	s_add_i32 s0, 0, 0x10018
	v_writelane_b32 v254, s0, 54
	s_add_i32 s0, 0, 0x1001c
	v_writelane_b32 v254, s0, 55
	s_add_i32 s0, 0, 0x10040
	v_writelane_b32 v254, s0, 56
	s_add_i32 s0, 0, 0x10020
	v_writelane_b32 v254, s0, 57
	s_add_i32 s0, 0, 0x10024
	v_writelane_b32 v254, s0, 58
	s_add_i32 s0, 0, 0x10028
	v_writelane_b32 v254, s0, 59
	s_add_i32 s0, 0, 0x1002c
	v_writelane_b32 v254, s0, 60
	s_add_i32 s0, 0, 0x10030
	v_writelane_b32 v254, s0, 61
	s_add_i32 s0, 0, 0x10034
	v_writelane_b32 v254, s0, 62
	s_add_i32 s0, 0, 0x10038
	v_writelane_b32 v254, s0, 63
	s_add_i32 s0, 0, 0x1003c
	v_writelane_b32 v255, s0, 0
	v_writelane_b32 v255, s16, 1
	s_mov_b32 s15, 0xc3dc0000
	s_mov_b32 s1, 0x41000000
	v_writelane_b32 v255, s17, 2
	s_mov_b64 s[16:17], 0
	v_writelane_b32 v255, s16, 3
	s_mov_b32 s18, 0x3fd744fd
	s_mov_b32 s0, 0xbcb8aa3b
	v_writelane_b32 v255, s17, 4
	s_lshl_b64 s[16:17], s[74:75], 2
	v_writelane_b32 v255, s16, 5
	s_brev_b32 s14, 34
	s_nop 0
	v_writelane_b32 v255, s17, 6
	s_mov_b64 s[16:17], 0x40000
	v_writelane_b32 v255, s16, 7
	s_nop 1
	v_writelane_b32 v255, s17, 8
	v_writelane_b32 v255, s60, 9
	s_nop 1
	v_writelane_b32 v255, s61, 10
	v_writelane_b32 v255, s62, 11
	s_nop 1
	v_writelane_b32 v255, s63, 12
	s_branch .LBB0_12

.LBB0_351:
	s_add_i32 s71, s71, 1
	s_mul_i32 s38, s71, s70
	s_mul_hi_u32 s39, s71, s3
	s_add_i32 s39, s39, s38
	s_mul_i32 s38, s71, s3
	s_add_u32 s50, s38, s2
	s_addc_u32 s51, s39, s73
	v_mov_b64_e32 v[0:1], 0x500
	v_cmp_lt_i64_e64 s[38:39], s[50:51], v[0:1]
	v_mov_b64_e32 v[0:1], 0x4ff
	v_cmp_gt_i64_e32 vcc, s[50:51], v[0:1]
	s_cbranch_vccnz .LBB0_353
	s_ashr_i32 s46, s50, 31
	s_lshr_b32 s46, s46, 29
	s_add_i32 s46, s50, s46
	s_ashr_i32 s47, s46, 3
	s_and_b32 s46, s46, -8
	s_sub_i32 s46, s50, s46
	s_cmp_lt_i32 s46, 0
	s_movk_i32 s48, 0xa1
	s_cselect_b32 s48, s48, 0xa0
	s_mul_i32 s46, s46, s48
	s_add_i32 s46, s46, s47
	s_ashr_i32 s47, s46, 31
	s_lshr_b32 s47, s47, 27
	s_add_i32 s47, s46, s47
	s_ashr_i32 s48, s47, 5
	s_lshl_b32 s48, s48, 3
	s_sub_i32 s49, 0x140, s48
	s_min_i32 s49, s49, 8
	s_abs_i32 s50, s49
	v_cvt_f32_u32_e32 v0, s50
	s_sub_i32 s52, 0, s50
	s_andn2_b32 s47, s47, 31
	s_sub_i32 s47, s46, s47
	v_rcp_iflag_f32_e32 v0, v0
	s_abs_i32 s46, s47
	s_xor_b32 s51, s47, s49
	s_ashr_i32 s51, s51, 31
	v_mul_f32_e32 v0, 0x4f7ffffe, v0
	v_cvt_u32_f32_e32 v0, v0
	s_nop 0
	v_readfirstlane_b32 s53, v0
	s_mul_i32 s52, s52, s53
	s_mul_hi_u32 s52, s53, s52
	s_add_i32 s53, s53, s52
	s_mul_hi_u32 s52, s46, s53
	s_mul_i32 s53, s52, s50
	s_sub_i32 s46, s46, s53
	s_add_i32 s54, s52, 1
	s_sub_i32 s53, s46, s50
	s_cmp_ge_u32 s46, s50
	s_cselect_b32 s52, s54, s52
	s_cselect_b32 s46, s53, s46
	s_add_i32 s53, s52, 1
	s_cmp_ge_u32 s46, s50
	s_cselect_b32 s46, s53, s52
	s_xor_b32 s46, s46, s51
	s_sub_i32 s46, s46, s51
	s_mul_i32 s49, s46, s49
	s_sub_i32 s47, s47, s49
	s_add_i32 s48, s48, s47
	s_mul_i32 s98, s48, 0xcccd
	s_lshr_b32 s98, s98, 21
	s_mul_i32 s98, s98, 0x50
	s_addk_i32 s98, 0x27
	s_sub_i32 s48, s98, s48
